# NSA selected-branch fast interior step accumulates PV in place (D=C) instead of into a second register set copied back with 24 moves per step
# speedup vs baseline: 1.0040x; 1.0040x over previous
.LBB0_1438:
	s_andn2_b64 vcc, exec, s[18:19]
	s_cbranch_vccnz .LBB0_1440
	ds_read_b128 v[56:59], v139
	ds_read_b128 v[60:63], v139 offset:64
	ds_read_b128 v[68:71], v139 offset:2304
	s_nop 2
	ds_read_b128 v[72:75], v139 offset:2368
	ds_read_b128 v[80:83], v139 offset:4608
	ds_read_b128 v[84:87], v139 offset:4672
	ds_read_b128 v[140:143], v139 offset:6912
	ds_read_b128 v[144:147], v139 offset:6976
	s_waitcnt lgkmcnt(7)
	v_mfma_f32_16x16x32_bf16 v[64:67], v[56:59], v[0:3], 0
	v_cmp_ne_u32_e32 vcc, 0, v137
	s_waitcnt lgkmcnt(5)
	v_mfma_f32_16x16x32_bf16 v[76:79], v[68:71], v[0:3], 0
	v_cndmask_b32_e32 v108, v118, v138, vcc
	v_cmp_ne_u32_e32 vcc, 0, v111
	v_add_u32_e32 v111, 0x1000, v110
	v_mfma_f32_16x16x32_bf16 v[64:67], v[60:63], v[4:7], v[64:67]
	s_waitcnt lgkmcnt(4)
	v_mfma_f32_16x16x32_bf16 v[76:79], v[72:75], v[4:7], v[76:79]
	v_mfma_f32_16x16x32_bf16 v[56:59], v[56:59], v[8:11], 0
	s_nop 4
	v_fma_f32 v138, v66, s86, -v108
	v_fma_f32 v139, v67, s86, -v108
	v_pk_fma_f32 v[148:149], v[64:65], s[86:87], v[108:109] op_sel_hi:[1,0,0] neg_lo:[0,0,1] neg_hi:[0,0,1]
	v_pk_fma_f32 v[152:153], v[78:79], s[86:87], v[108:109] op_sel_hi:[1,0,0] neg_lo:[0,0,1] neg_hi:[0,0,1]
	s_waitcnt lgkmcnt(3)
	v_mfma_f32_16x16x32_bf16 v[64:67], v[80:83], v[0:3], 0
	v_fma_f32 v154, v76, s86, -v108
	v_fma_f32 v155, v77, s86, -v108
	v_exp_f32_e32 v148, v148
	v_exp_f32_e32 v149, v149
	s_waitcnt lgkmcnt(1)
	v_mfma_f32_16x16x32_bf16 v[76:79], v[140:143], v[0:3], 0
	v_exp_f32_e32 v138, v138
	v_exp_f32_e32 v139, v139
	v_exp_f32_e32 v154, v154
	v_mfma_f32_16x16x32_bf16 v[64:67], v[84:87], v[4:7], v[64:67]
	v_exp_f32_e32 v155, v155
	v_exp_f32_e32 v152, v152
	v_exp_f32_e32 v153, v153
	s_waitcnt lgkmcnt(0)
	v_mfma_f32_16x16x32_bf16 v[76:79], v[144:147], v[4:7], v[76:79]
	v_add_f32_e64 v150, v148, 0
	v_add_f32_e64 v151, v149, 0
	s_nop 0
	v_pk_fma_f32 v[66:67], v[66:67], s[86:87], v[108:109] op_sel_hi:[1,0,0] neg_lo:[0,0,1] neg_hi:[0,0,1]
	v_pk_fma_f32 v[64:65], v[64:65], s[86:87], v[108:109] op_sel_hi:[1,0,0] neg_lo:[0,0,1] neg_hi:[0,0,1]
	v_mfma_f32_16x16x32_bf16 v[56:59], v[60:63], v[12:15], v[56:59]
	v_exp_f32_e32 v158, v64
	v_exp_f32_e32 v159, v65
	v_exp_f32_e32 v160, v66
	v_mfma_f32_16x16x32_bf16 v[60:63], v[68:71], v[8:11], 0
	v_exp_f32_e32 v161, v67
	v_pk_fma_f32 v[70:71], v[78:79], s[86:87], v[108:109] op_sel_hi:[1,0,0] neg_lo:[0,0,1] neg_hi:[0,0,1]
	v_pk_add_f32 v[156:157], v[138:139], 0 op_sel_hi:[1,0]
	v_mfma_f32_16x16x32_bf16 v[60:63], v[72:75], v[12:15], v[60:63]
	v_fma_f32 v72, v76, s86, -v108
	v_fma_f32 v73, v77, s86, -v108
	v_exp_f32_e32 v108, v70
	v_exp_f32_e32 v74, v72
	v_mfma_f32_16x16x32_bf16 v[64:67], v[80:83], v[8:11], 0
	v_exp_f32_e32 v75, v73
	v_exp_f32_e32 v109, v71
	v_pk_add_f32 v[150:151], v[150:151], v[154:155]
	v_pk_add_f32 v[156:157], v[156:157], v[152:153]
	v_pk_add_f32 v[68:69], v[150:151], v[158:159]
	v_mfma_f32_16x16x32_bf16 v[64:67], v[84:87], v[12:15], v[64:67]
	v_cndmask_b32_e32 v86, v118, v136, vcc
	v_pk_add_f32 v[70:71], v[156:157], v[160:161]
	v_pk_add_f32 v[68:69], v[68:69], v[74:75]
	v_pk_fma_f32 v[58:59], v[58:59], s[86:87], v[86:87] op_sel_hi:[1,0,0] neg_lo:[0,0,1] neg_hi:[0,0,1]
	v_pk_fma_f32 v[56:57], v[56:57], s[86:87], v[86:87] op_sel_hi:[1,0,0] neg_lo:[0,0,1] neg_hi:[0,0,1]
	v_pk_add_f32 v[84:85], v[70:71], v[108:109]
	v_add_f32_e32 v150, v68, v69
	v_mfma_f32_16x16x32_bf16 v[68:71], v[140:143], v[8:11], 0
	v_exp_f32_e32 v140, v56
	v_exp_f32_e32 v141, v57
	v_exp_f32_e32 v142, v58
	v_exp_f32_e32 v143, v59
	ds_read2_b64 v[56:59], v110 offset1:4
	v_pk_fma_f32 v[62:63], v[62:63], s[86:87], v[86:87] op_sel_hi:[1,0,0] neg_lo:[0,0,1] neg_hi:[0,0,1]
	v_pk_fma_f32 v[60:61], v[60:61], s[86:87], v[86:87] op_sel_hi:[1,0,0] neg_lo:[0,0,1] neg_hi:[0,0,1]
	v_mfma_f32_16x16x32_bf16 v[68:71], v[144:147], v[12:15], v[68:71]
	v_exp_f32_e32 v144, v60
	v_exp_f32_e32 v145, v61
	v_exp_f32_e32 v146, v62
	v_exp_f32_e32 v147, v63
	v_cvt_pk_bf16_f32 v76, v148, v149
	v_cvt_pk_bf16_f32 v77, v138, v139
	v_cvt_pk_bf16_f32 v78, v154, v155
	v_cvt_pk_bf16_f32 v79, v152, v153
	v_cvt_pk_bf16_f32 v60, v140, v141
	v_cvt_pk_bf16_f32 v61, v142, v143
	v_cvt_pk_bf16_f32 v62, v144, v145
	v_cvt_pk_bf16_f32 v63, v146, v147
	s_waitcnt lgkmcnt(0)
	v_mfma_f32_16x16x32_bf16 v[52:55], v[56:59], v[76:79], v[52:55]
	v_add_u32_e32 v87, 0x800, v110
	v_add_u32_e32 v148, 0x1800, v110
	ds_read2_b64 v[80:83], v87 offset0:32 offset1:36
	v_mfma_f32_16x16x32_bf16 v[48:51], v[56:59], v[60:63], v[48:51]
	ds_read2_b64 v[56:59], v111 offset0:64 offset1:68
	v_cvt_pk_bf16_f32 v74, v74, v75
	v_cvt_pk_bf16_f32 v75, v108, v109
	v_pk_fma_f32 v[108:109], v[66:67], s[86:87], v[86:87] op_sel_hi:[1,0,0] neg_lo:[0,0,1] neg_hi:[0,0,1]
	v_pk_fma_f32 v[136:137], v[64:65], s[86:87], v[86:87] op_sel_hi:[1,0,0] neg_lo:[0,0,1] neg_hi:[0,0,1]
	ds_read2_b64 v[64:67], v148 offset0:96 offset1:100
	s_waitcnt lgkmcnt(1)
	v_mfma_f32_16x16x32_bf16 v[36:39], v[56:59], v[76:79], v[36:39]
	v_fma_f32 v70, v70, s86, -v86
	v_fma_f32 v71, v71, s86, -v86
	v_pk_fma_f32 v[68:69], v[68:69], s[86:87], v[86:87] op_sel_hi:[1,0,0] neg_lo:[0,0,1] neg_hi:[0,0,1]
	v_exp_f32_e32 v70, v70
	v_mfma_f32_16x16x32_bf16 v[32:35], v[56:59], v[60:63], v[32:35]
	ds_read2_b64 v[56:59], v110 offset0:8 offset1:12
	v_exp_f32_e32 v68, v68
	v_exp_f32_e32 v69, v69
	v_mfma_f32_16x16x32_bf16 v[40:43], v[80:83], v[60:63], v[40:43]
	v_exp_f32_e32 v71, v71
	v_cvt_pk_bf16_f32 v72, v158, v159
	v_cvt_pk_bf16_f32 v73, v160, v161
	s_waitcnt lgkmcnt(1)
	v_mfma_f32_16x16x32_bf16 v[24:27], v[64:67], v[60:63], v[24:27]
	ds_read2_b64 v[60:63], v87 offset0:40 offset1:44
	v_cvt_pk_bf16_f32 v138, v68, v69
	v_cvt_pk_bf16_f32 v139, v70, v71
	v_mfma_f32_16x16x32_bf16 v[44:47], v[80:83], v[76:79], v[44:47]
	v_exp_f32_e32 v80, v136
	v_exp_f32_e32 v81, v137
	v_exp_f32_e32 v82, v108
	v_exp_f32_e32 v83, v109
	v_mfma_f32_16x16x32_bf16 v[28:31], v[64:67], v[76:79], v[28:31]
	v_cvt_pk_bf16_f32 v136, v80, v81
	v_cvt_pk_bf16_f32 v137, v82, v83
	s_waitcnt lgkmcnt(1)
	v_mfma_f32_16x16x32_bf16 v[52:55], v[56:59], v[72:75], v[52:55]
	v_mfma_f32_16x16x32_bf16 v[48:51], v[56:59], v[136:139], v[48:51]
	v_add_f32_e64 v200, v142, 0
	v_add_f32_e64 v201, v143, 0
	v_add_f32_e32 v202, v84, v85
	ds_read2_b64 v[204:207], v111 offset0:72 offset1:76
	s_waitcnt lgkmcnt(1)
	v_mfma_f32_16x16x32_bf16 v[44:47], v[60:63], v[72:75], v[44:47]
	v_mfma_f32_16x16x32_bf16 v[40:43], v[60:63], v[136:139], v[40:43]
	v_add_f32_e64 v208, v140, 0
	v_add_f32_e64 v209, v141, 0
	v_pk_add_f32 v[210:211], v[200:201], v[146:147]
	v_pk_add_f32 v[208:209], v[208:209], v[144:145]
	ds_read2_b64 v[212:215], v148 offset0:104 offset1:108
	v_pk_add_f32 v[210:211], v[210:211], v[82:83]
	v_pk_add_f32 v[208:209], v[208:209], v[80:81]
	s_waitcnt lgkmcnt(1)
	v_mfma_f32_16x16x32_bf16 v[36:39], v[204:207], v[72:75], v[36:39]
	v_add_f32_e64 v216, v208, v68
	v_add_f32_e64 v217, v209, v69
	v_pk_add_f32 v[218:219], v[210:211], v[70:71]
	v_mfma_f32_16x16x32_bf16 v[32:35], v[204:207], v[136:139], v[32:35]
	v_pk_mov_b32 v[208:209], v[216:217], v[218:219] op_sel:[1,0]
	v_mov_b32_e32 v217, v219
	s_nop 0
	v_pk_add_f32 v[220:221], v[208:209], v[216:217]
	s_waitcnt lgkmcnt(0)
	v_mfma_f32_16x16x32_bf16 v[28:31], v[212:215], v[72:75], v[28:31]
	v_mov_b32_e32 v151, v220
	v_mov_b32_e32 v203, v221
	v_mfma_f32_16x16x32_bf16 v[24:27], v[212:215], v[136:139], v[24:27]
	v_add_f32_e64 v222, v150, v202
	v_add_f32_e64 v223, v151, v203
	v_pk_add_f32 v[104:105], v[104:105], v[222:223]
	s_branch .LBB0_1442
